# prep mod-GEMV k-loop: next k-step's 16 strided weight loads issued one iteration ahead
# baseline (speedup 1.0000x reference)
; DI void ph_prep(const Params& p, unsigned char* smem, int bid, int nb) {
;     ...
;       const int jj = tid & 31, kq = tid >> 5;
;       const int j = jc * 32 + jj;
;       float acc[9];
; #pragma unroll
;       for (int rr = 0; rr < 9; ++rr) acc[rr] = 0.f;
;       const float* wm = p.w_mod + (size_t)l * DM * 3072 + j;
; #pragma unroll 1
;       for (int k0 = kq * 128; k0 < kq * 128 + 128; k0 += 16) {
;         float w[16];
; #pragma unroll
;         for (int u = 0; u < 16; ++u) w[u] = wm[(size_t)(k0 + u) * 3072];
.LBB0_49:
	s_or_b64 exec, exec, s[10:11]
	s_mul_hi_i32 s1, s0, 0x2aaaaaab
	s_lshr_b32 s10, s1, 31
	s_ashr_i32 s1, s1, 4
	s_add_i32 s1, s1, s10
	s_mul_i32 s10, s1, 0x60
	s_sub_i32 s10, s0, s10
	s_lshl_b32 s10, s10, 5
	v_or_b32_e32 v0, s10, v111
	v_ashrrev_i32_e32 v1, 31, v0
	v_lshlrev_b64 v[0:1], 2, v[0:1]
	v_mad_i64_i32 v[0:1], s[12:13], s1, v143, v[0:1]
	v_lshl_add_u64 v[96:97], v[60:61], 0, v[0:1]
	v_mov_b32_e32 v0, 0
	s_mov_b32 s52, 0x6a5dcb37
	s_mov_b32 s54, 0x6dc9c883
	s_mov_b32 s56, 0x252049c0
	s_mov_b32 s58, 0x9037ab78
	s_mov_b32 s60, 0xb42fdfa7
	s_mov_b64 s[12:13], 0
	v_mov_b32_e32 v146, v132
	v_mov_b32_e32 v147, v45
	v_mov_b32_e32 v1, v0
	v_mov_b32_e32 v8, v0
	v_mov_b32_e32 v9, v0
	v_mov_b32_e32 v98, v0
	v_mov_b32_e32 v99, v0
	v_mov_b32_e32 v100, v0
	v_mov_b32_e32 v101, v0
	v_mov_b32_e32 v103, v0
	s_mov_b32 s53, 0x3e5ade15
	s_mov_b32 s55, 0x3fe45f30
	s_mov_b32 s57, 0xb97b839a
	s_mov_b32 s59, 0x3e21eeb6
	s_mov_b32 s61, 0xbe5ae600
	s_waitcnt lgkmcnt(0)
	s_barrier
	v_add_co_u32_e32 v2, vcc, 0xfffd3000, v96
	s_nop 1
	v_addc_co_u32_e32 v3, vcc, -1, v97, vcc
	global_load_dword v196, v[2:3], off
	v_add_co_u32_e32 v2, vcc, 0xfffd6000, v96
	s_nop 1
	v_addc_co_u32_e32 v3, vcc, -1, v97, vcc
	global_load_dword v197, v[2:3], off
	v_add_co_u32_e32 v2, vcc, 0xfffd9000, v96
	s_nop 1
	v_addc_co_u32_e32 v3, vcc, -1, v97, vcc
	global_load_dword v198, v[2:3], off
	v_add_co_u32_e32 v2, vcc, 0xfffdc000, v96
	s_nop 1
	v_addc_co_u32_e32 v3, vcc, -1, v97, vcc
	global_load_dword v199, v[2:3], off
	v_add_co_u32_e32 v2, vcc, 0xfffdf000, v96
	s_nop 1
	v_addc_co_u32_e32 v3, vcc, -1, v97, vcc
	global_load_dword v200, v[2:3], off
	v_add_co_u32_e32 v2, vcc, 0xfffe2000, v96
	s_nop 1
	v_addc_co_u32_e32 v3, vcc, -1, v97, vcc
	global_load_dword v201, v[2:3], off
	v_add_co_u32_e32 v2, vcc, 0xfffe5000, v96
	s_nop 1
	v_addc_co_u32_e32 v3, vcc, -1, v97, vcc
	global_load_dword v202, v[2:3], off
	v_add_co_u32_e32 v2, vcc, 0xfffe8000, v96
	s_nop 1
	v_addc_co_u32_e32 v3, vcc, -1, v97, vcc
	global_load_dword v203, v[2:3], off
	v_add_co_u32_e32 v2, vcc, 0xfffeb000, v96
	s_nop 1
	v_addc_co_u32_e32 v3, vcc, -1, v97, vcc
	global_load_dword v204, v[2:3], off
	v_add_co_u32_e32 v2, vcc, 0xfffee000, v96
	s_nop 1
	v_addc_co_u32_e32 v3, vcc, -1, v97, vcc
	global_load_dword v205, v[2:3], off
	v_add_co_u32_e32 v2, vcc, 0xffff1000, v96
	s_nop 1
	v_addc_co_u32_e32 v3, vcc, -1, v97, vcc
	global_load_dword v206, v[2:3], off
	v_add_co_u32_e32 v2, vcc, 0xffff4000, v96
	s_nop 1
	v_addc_co_u32_e32 v3, vcc, -1, v97, vcc
	global_load_dword v207, v[2:3], off
	v_add_co_u32_e32 v2, vcc, 0xffff7000, v96
	s_nop 1
	v_addc_co_u32_e32 v3, vcc, -1, v97, vcc
	global_load_dword v208, v[2:3], off
	v_add_co_u32_e32 v2, vcc, 0xffffa000, v96
	s_nop 1
	v_addc_co_u32_e32 v3, vcc, -1, v97, vcc
	global_load_dword v209, v[2:3], off
	v_add_co_u32_e32 v2, vcc, 0xffffd000, v96
	s_nop 1
	v_addc_co_u32_e32 v3, vcc, -1, v97, vcc
	global_load_dword v210, v[2:3], off
	global_load_dword v211, v[96:97], off
.LBB0_50:
	s_waitcnt vmcnt(0)
	v_mov_b32_e32 v114, v196
	v_mov_b32_e32 v116, v197
	v_mov_b32_e32 v118, v198
	v_mov_b32_e32 v120, v199
	v_mov_b32_e32 v10, v200
	v_mov_b32_e32 v110, v201
	v_mov_b32_e32 v112, v202
	v_mov_b32_e32 v113, v203
	v_mov_b32_e32 v106, v204
	v_mov_b32_e32 v107, v205
	v_mov_b32_e32 v108, v206
	v_mov_b32_e32 v109, v207
	v_mov_b32_e32 v104, v208
	v_mov_b32_e32 v105, v209
	v_mov_b32_e32 v102, v210
	v_mov_b32_e32 v48, v211
	v_add_u32_e32 v147, 16, v147
	s_mov_b64 s[88:89], 0x30000
	v_lshl_add_u64 v[96:97], v[96:97], 0, s[88:89]
	v_cmp_ge_i32_e32 vcc, v147, v130
	s_or_b64 s[12:13], vcc, s[12:13]
	s_cbranch_vccnz .Lmod_noload
	v_add_co_u32_e32 v2, vcc, 0xfffd3000, v96
	s_nop 1
	v_addc_co_u32_e32 v3, vcc, -1, v97, vcc
	global_load_dword v196, v[2:3], off
	v_add_co_u32_e32 v2, vcc, 0xfffd6000, v96
	s_nop 1
	v_addc_co_u32_e32 v3, vcc, -1, v97, vcc
	global_load_dword v197, v[2:3], off
	v_add_co_u32_e32 v2, vcc, 0xfffd9000, v96
	s_nop 1
	v_addc_co_u32_e32 v3, vcc, -1, v97, vcc
	global_load_dword v198, v[2:3], off
	v_add_co_u32_e32 v2, vcc, 0xfffdc000, v96
	s_nop 1
	v_addc_co_u32_e32 v3, vcc, -1, v97, vcc
	global_load_dword v199, v[2:3], off
	v_add_co_u32_e32 v2, vcc, 0xfffdf000, v96
	s_nop 1
	v_addc_co_u32_e32 v3, vcc, -1, v97, vcc
	global_load_dword v200, v[2:3], off
	v_add_co_u32_e32 v2, vcc, 0xfffe2000, v96
	s_nop 1
	v_addc_co_u32_e32 v3, vcc, -1, v97, vcc
	global_load_dword v201, v[2:3], off
	v_add_co_u32_e32 v2, vcc, 0xfffe5000, v96
	s_nop 1
	v_addc_co_u32_e32 v3, vcc, -1, v97, vcc
	global_load_dword v202, v[2:3], off
	v_add_co_u32_e32 v2, vcc, 0xfffe8000, v96
	s_nop 1
	v_addc_co_u32_e32 v3, vcc, -1, v97, vcc
	global_load_dword v203, v[2:3], off
	v_add_co_u32_e32 v2, vcc, 0xfffeb000, v96
	s_nop 1
	v_addc_co_u32_e32 v3, vcc, -1, v97, vcc
	global_load_dword v204, v[2:3], off
	v_add_co_u32_e32 v2, vcc, 0xfffee000, v96
	s_nop 1
	v_addc_co_u32_e32 v3, vcc, -1, v97, vcc
	global_load_dword v205, v[2:3], off
	v_add_co_u32_e32 v2, vcc, 0xffff1000, v96
	s_nop 1
	v_addc_co_u32_e32 v3, vcc, -1, v97, vcc
	global_load_dword v206, v[2:3], off
	v_add_co_u32_e32 v2, vcc, 0xffff4000, v96
	s_nop 1
	v_addc_co_u32_e32 v3, vcc, -1, v97, vcc
	global_load_dword v207, v[2:3], off
	v_add_co_u32_e32 v2, vcc, 0xffff7000, v96
	s_nop 1
	v_addc_co_u32_e32 v3, vcc, -1, v97, vcc
	global_load_dword v208, v[2:3], off
	v_add_co_u32_e32 v2, vcc, 0xffffa000, v96
	s_nop 1
	v_addc_co_u32_e32 v3, vcc, -1, v97, vcc
	global_load_dword v209, v[2:3], off
	v_add_co_u32_e32 v2, vcc, 0xffffd000, v96
	s_nop 1
	v_addc_co_u32_e32 v3, vcc, -1, v97, vcc
	global_load_dword v210, v[2:3], off
	global_load_dword v211, v[96:97], off
; DI void ph_prep(const Params& p, unsigned char* smem, int bid, int nb) {
;     ...
;       for (int k0 = kq * 128; k0 < kq * 128 + 128; k0 += 16) {
;         float w[16];
; #pragma unroll
;         for (int u = 0; u < 16; ++u) w[u] = wm[(size_t)(k0 + u) * 3072];
; #pragma unroll
;         for (int u = 0; u < 16; ++u)
; #pragma unroll
;           for (int rr = 0; rr < 9; ++rr) acc[rr] += sc[rr * 1024 + k0 + u] * w[u];
.Lmod_noload:
	ds_read_b128 v[2:5], v146 offset:32768
	s_waitcnt lgkmcnt(0)
	v_fmac_f32_e32 v103, v114, v2
	s_nop 0
	v_fmac_f32_e32 v103, v116, v3
	s_nop 0
	v_fmac_f32_e32 v103, v118, v4
	s_nop 0
	v_fmac_f32_e32 v103, v120, v5
	ds_read_b128 v[2:5], v146
	ds_read_b128 v[36:39], v146 offset:16
	ds_read_b128 v[24:27], v146 offset:32
	ds_read_b128 v[12:15], v146 offset:48
	ds_read_b128 v[40:43], v146 offset:4112
	ds_read_b128 v[16:19], v146 offset:4096
	s_waitcnt lgkmcnt(5)
	v_mov_b32_e32 v6, v2
	v_mov_b32_e32 v2, v4
	s_waitcnt lgkmcnt(0)
	v_mov_b32_e32 v7, v16
	v_pk_fma_f32 v[0:1], v[114:115], v[6:7], v[0:1] op_sel_hi:[0,1,1]
	v_mov_b32_e32 v16, v3
	v_pk_fma_f32 v[0:1], v[116:117], v[16:17], v[0:1] op_sel_hi:[0,1,1]
	v_mov_b32_e32 v3, v18
	v_pk_fma_f32 v[0:1], v[118:119], v[2:3], v[0:1] op_sel_hi:[0,1,1]
	v_mov_b32_e32 v18, v5
	v_pk_fma_f32 v[0:1], v[120:121], v[18:19], v[0:1] op_sel_hi:[0,1,1]
	v_mov_b32_e32 v2, v36
	v_mov_b32_e32 v3, v40
	s_nop 0
	v_pk_fma_f32 v[124:125], v[10:11], v[2:3], v[0:1] op_sel_hi:[0,1,1]
	ds_read_b128 v[28:31], v146 offset:8208
	ds_read_b128 v[32:35], v146 offset:12304
	ds_read_b128 v[0:3], v146 offset:8192
	ds_read_b128 v[4:7], v146 offset:12288
	v_mov_b32_e32 v40, v37
	s_waitcnt lgkmcnt(1)
	v_mov_b32_e32 v16, v0
	s_waitcnt lgkmcnt(0)
	v_mov_b32_e32 v17, v4
	v_pk_fma_f32 v[8:9], v[114:115], v[16:17], v[8:9] op_sel_hi:[0,1,1]
	v_mov_b32_e32 v4, v1
	v_pk_fma_f32 v[0:1], v[116:117], v[4:5], v[8:9] op_sel_hi:[0,1,1]
	v_mov_b32_e32 v4, v2
	v_mov_b32_e32 v5, v6
	v_pk_fma_f32 v[0:1], v[118:119], v[4:5], v[0:1] op_sel_hi:[0,1,1]
	v_mov_b32_e32 v6, v3
	v_pk_fma_f32 v[0:1], v[120:121], v[6:7], v[0:1] op_sel_hi:[0,1,1]
	v_mov_b32_e32 v2, v28
	v_mov_b32_e32 v3, v32
	v_pk_fma_f32 v[122:123], v[10:11], v[2:3], v[0:1] op_sel_hi:[0,1,1]
	ds_read_b128 v[16:19], v146 offset:16400
	ds_read_b128 v[20:23], v146 offset:20496
	ds_read_b128 v[0:3], v146 offset:16384
	ds_read_b128 v[4:7], v146 offset:20480
	s_nop 0
	v_mov_b32_e32 v28, v113
	v_mov_b32_e32 v32, v29
	s_waitcnt lgkmcnt(1)
	v_mov_b32_e32 v8, v0
	s_waitcnt lgkmcnt(0)
	v_mov_b32_e32 v9, v4
	v_pk_fma_f32 v[8:9], v[114:115], v[8:9], v[98:99] op_sel_hi:[0,1,1]
	v_mov_b32_e32 v4, v1
	v_pk_fma_f32 v[0:1], v[116:117], v[4:5], v[8:9] op_sel_hi:[0,1,1]
	v_mov_b32_e32 v4, v2
	v_mov_b32_e32 v5, v6
	v_pk_fma_f32 v[0:1], v[118:119], v[4:5], v[0:1] op_sel_hi:[0,1,1]
	v_mov_b32_e32 v6, v3
	v_pk_fma_f32 v[0:1], v[120:121], v[6:7], v[0:1] op_sel_hi:[0,1,1]
	v_mov_b32_e32 v2, v16
	v_mov_b32_e32 v3, v20
	v_pk_fma_f32 v[98:99], v[10:11], v[2:3], v[0:1] op_sel_hi:[0,1,1]
	ds_read_b128 v[0:3], v146 offset:24592
	ds_read_b128 v[4:7], v146 offset:28688
	ds_read_b128 v[148:151], v146 offset:24576
	ds_read_b128 v[152:155], v146 offset:28672
	v_mov_b32_e32 v20, v17
	s_waitcnt lgkmcnt(1)
	v_mov_b32_e32 v8, v148
	s_waitcnt lgkmcnt(0)
	v_mov_b32_e32 v9, v152
	v_pk_fma_f32 v[8:9], v[114:115], v[8:9], v[100:101] op_sel_hi:[0,1,1]
	v_mov_b32_e32 v152, v149
	v_mov_b32_e32 v100, v150
	v_mov_b32_e32 v101, v154
	v_mov_b32_e32 v154, v151
	ds_read_b128 v[148:151], v146 offset:32784
	v_pk_fma_f32 v[8:9], v[116:117], v[152:153], v[8:9] op_sel_hi:[0,1,1]
	v_pk_fma_f32 v[8:9], v[118:119], v[100:101], v[8:9] op_sel_hi:[0,1,1]
	v_pk_fma_f32 v[8:9], v[120:121], v[154:155], v[8:9] op_sel_hi:[0,1,1]
	v_mov_b32_e32 v100, v0
	v_mov_b32_e32 v101, v4
	v_pk_fma_f32 v[100:101], v[10:11], v[100:101], v[8:9] op_sel_hi:[0,1,1]
	v_mov_b32_e32 v11, v110
	v_mov_b32_e32 v4, v1
	s_waitcnt lgkmcnt(0)
	v_pk_mul_f32 v[0:1], v[10:11], v[148:149]
	v_pk_fma_f32 v[4:5], v[110:111], v[4:5], v[100:101] op_sel_hi:[0,1,1]
	v_add_f32_e32 v0, v103, v0
	v_add_f32_e32 v8, v0, v1
	v_pk_mul_f32 v[0:1], v[112:113], v[150:151]
	s_nop 0
	v_add_f32_e32 v0, v8, v0
	ds_read_b128 v[8:11], v146 offset:32800
	v_add_f32_e32 v16, v0, v1
	s_waitcnt lgkmcnt(0)
	v_pk_mul_f32 v[0:1], v[106:107], v[8:9]
	s_nop 0
	v_add_f32_e32 v0, v16, v0
	v_add_f32_e32 v8, v0, v1
	s_nop 0
	v_pk_mul_f32 v[0:1], v[108:109], v[10:11]
	s_nop 0
	v_add_f32_e32 v0, v8, v0
	ds_read_b128 v[8:11], v146 offset:32816
	v_add_f32_e32 v16, v0, v1
	s_waitcnt lgkmcnt(0)
	v_pk_mul_f32 v[0:1], v[104:105], v[8:9]
	v_mov_b32_e32 v8, v38
	v_mov_b32_e32 v9, v42
	v_mov_b32_e32 v42, v39
	ds_read_b128 v[36:39], v146 offset:4128
	v_add_f32_e32 v0, v16, v0
	v_add_f32_e32 v17, v0, v1
	v_pk_fma_f32 v[0:1], v[110:111], v[40:41], v[124:125] op_sel_hi:[0,1,1]
	v_pk_fma_f32 v[0:1], v[112:113], v[8:9], v[0:1] op_sel_hi:[0,1,1]
	v_pk_fma_f32 v[0:1], v[28:29], v[42:43], v[0:1] op_sel_hi:[0,1,1]
	v_mov_b32_e32 v8, v24
	s_waitcnt lgkmcnt(0)
	v_mov_b32_e32 v9, v36
	v_pk_fma_f32 v[0:1], v[106:107], v[8:9], v[0:1] op_sel_hi:[0,1,1]
	v_mov_b32_e32 v16, v107
	v_mov_b32_e32 v36, v25
	v_pk_fma_f32 v[0:1], v[16:17], v[36:37], v[0:1] op_sel_hi:[0,1,1]
	v_mov_b32_e32 v8, v26
	v_mov_b32_e32 v9, v38
	v_pk_fma_f32 v[0:1], v[108:109], v[8:9], v[0:1] op_sel_hi:[0,1,1]
	v_mov_b32_e32 v24, v109
	v_mov_b32_e32 v38, v27
	v_pk_fma_f32 v[0:1], v[24:25], v[38:39], v[0:1] op_sel_hi:[0,1,1]
	ds_read_b128 v[36:39], v146 offset:4144
	v_mov_b32_e32 v8, v12
	v_mov_b32_e32 v12, v105
	s_waitcnt lgkmcnt(0)
	v_mov_b32_e32 v9, v36
	v_pk_fma_f32 v[0:1], v[104:105], v[8:9], v[0:1] op_sel_hi:[0,1,1]
	v_mov_b32_e32 v36, v13
	v_pk_fma_f32 v[0:1], v[12:13], v[36:37], v[0:1] op_sel_hi:[0,1,1]
	v_mov_b32_e32 v8, v14
	v_mov_b32_e32 v9, v38
	s_nop 0
	v_pk_fma_f32 v[0:1], v[102:103], v[8:9], v[0:1] op_sel_hi:[0,1,1]
	v_mov_b32_e32 v38, v15
	v_pk_fma_f32 v[8:9], v[110:111], v[32:33], v[122:123] op_sel_hi:[0,1,1]
	v_mov_b32_e32 v14, v30
	v_mov_b32_e32 v15, v34
	v_pk_fma_f32 v[8:9], v[112:113], v[14:15], v[8:9] op_sel_hi:[0,1,1]
	v_mov_b32_e32 v34, v31
	v_pk_fma_f32 v[8:9], v[28:29], v[34:35], v[8:9] op_sel_hi:[0,1,1]
	ds_read_b128 v[30:33], v146 offset:8224
	ds_read_b128 v[34:37], v146 offset:12320
	s_nop 0
	v_pk_fma_f32 v[0:1], v[48:49], v[38:39], v[0:1] op_sel_hi:[0,1,1]
	s_waitcnt lgkmcnt(1)
; DI void ph_prep(const Params& p, unsigned char* smem, int bid, int nb) {
;     ...
; #pragma unroll
;         for (int u = 0; u < 16; ++u)
; #pragma unroll
;           for (int rr = 0; rr < 9; ++rr) acc[rr] += sc[rr * 1024 + k0 + u] * w[u];
;       }
;       __syncthreads();
;       float* red = (float*)smem;
; #pragma unroll
;       for (int rr = 0; rr < 9; ++rr) red[(kq * 9 + rr) * 32 + jj] = acc[rr];
;       __syncthreads();
;       for (int e = tid; e < 9 * 32; e += 256) {
;         const int rr = e >> 5, j2 = e & 31;
;         float s = 0.f;
; #pragma unroll
;         for (int q8 = 0; q8 < 8; ++q8) s += red[(q8 * 9 + rr) * 32 + j2];
;         MOD[((size_t)l * 9 + rr) * 3072 + jc * 32 + j2] = s + p.b_mod[l * 3072 + jc * 32 + j2];
	v_mov_b32_e32 v14, v30
	s_waitcnt lgkmcnt(0)
	v_mov_b32_e32 v15, v34
	v_pk_fma_f32 v[8:9], v[106:107], v[14:15], v[8:9] op_sel_hi:[0,1,1]
	v_mov_b32_e32 v34, v31
	v_pk_fma_f32 v[8:9], v[16:17], v[34:35], v[8:9] op_sel_hi:[0,1,1]
	v_mov_b32_e32 v14, v32
	v_mov_b32_e32 v15, v36
	v_pk_fma_f32 v[8:9], v[108:109], v[14:15], v[8:9] op_sel_hi:[0,1,1]
	v_mov_b32_e32 v36, v33
	v_pk_fma_f32 v[8:9], v[24:25], v[36:37], v[8:9] op_sel_hi:[0,1,1]
	ds_read_b128 v[30:33], v146 offset:8240
	ds_read_b128 v[34:37], v146 offset:12336
	s_waitcnt lgkmcnt(1)
	v_mov_b32_e32 v14, v30
	s_waitcnt lgkmcnt(0)
	v_mov_b32_e32 v15, v34
	v_pk_fma_f32 v[8:9], v[104:105], v[14:15], v[8:9] op_sel_hi:[0,1,1]
	v_mov_b32_e32 v34, v31
	v_pk_fma_f32 v[8:9], v[12:13], v[34:35], v[8:9] op_sel_hi:[0,1,1]
	v_mov_b32_e32 v14, v32
	v_mov_b32_e32 v15, v36
	v_pk_fma_f32 v[8:9], v[102:103], v[14:15], v[8:9] op_sel_hi:[0,1,1]
	v_pk_fma_f32 v[14:15], v[110:111], v[20:21], v[98:99] op_sel_hi:[0,1,1]
	v_mov_b32_e32 v20, v18
	v_mov_b32_e32 v21, v22
	v_mov_b32_e32 v36, v33
	v_pk_fma_f32 v[14:15], v[112:113], v[20:21], v[14:15] op_sel_hi:[0,1,1]
	v_mov_b32_e32 v22, v19
	ds_read_b128 v[18:21], v146 offset:16416
	ds_read_b128 v[30:33], v146 offset:20512
	v_pk_fma_f32 v[14:15], v[28:29], v[22:23], v[14:15] op_sel_hi:[0,1,1]
	v_pk_fma_f32 v[8:9], v[48:49], v[36:37], v[8:9] op_sel_hi:[0,1,1]
	s_waitcnt lgkmcnt(1)
	v_mov_b32_e32 v22, v18
	s_waitcnt lgkmcnt(0)
	v_mov_b32_e32 v23, v30
	v_pk_fma_f32 v[14:15], v[106:107], v[22:23], v[14:15] op_sel_hi:[0,1,1]
	v_mov_b32_e32 v30, v19
	v_pk_fma_f32 v[14:15], v[16:17], v[30:31], v[14:15] op_sel_hi:[0,1,1]
	v_mov_b32_e32 v18, v20
	v_mov_b32_e32 v19, v32
	v_pk_fma_f32 v[14:15], v[108:109], v[18:19], v[14:15] op_sel_hi:[0,1,1]
	v_mov_b32_e32 v32, v21
	v_pk_fma_f32 v[14:15], v[24:25], v[32:33], v[14:15] op_sel_hi:[0,1,1]
	ds_read_b128 v[18:21], v146 offset:16432
	ds_read_b128 v[30:33], v146 offset:20528
	s_waitcnt lgkmcnt(1)
	v_mov_b32_e32 v22, v18
	s_waitcnt lgkmcnt(0)
	v_mov_b32_e32 v23, v30
	v_pk_fma_f32 v[14:15], v[104:105], v[22:23], v[14:15] op_sel_hi:[0,1,1]
	v_mov_b32_e32 v30, v19
	v_pk_fma_f32 v[14:15], v[12:13], v[30:31], v[14:15] op_sel_hi:[0,1,1]
	v_mov_b32_e32 v18, v20
	v_mov_b32_e32 v19, v32
	v_pk_fma_f32 v[14:15], v[102:103], v[18:19], v[14:15] op_sel_hi:[0,1,1]
	v_mov_b32_e32 v32, v21
	v_pk_fma_f32 v[98:99], v[48:49], v[32:33], v[14:15] op_sel_hi:[0,1,1]
	v_mov_b32_e32 v14, v2
	v_mov_b32_e32 v15, v6
	v_pk_fma_f32 v[4:5], v[112:113], v[14:15], v[4:5] op_sel_hi:[0,1,1]
	v_mov_b32_e32 v6, v3
	v_pk_fma_f32 v[6:7], v[28:29], v[6:7], v[4:5] op_sel_hi:[0,1,1]
	ds_read_b128 v[2:5], v146 offset:24608
	ds_read_b128 v[18:21], v146 offset:28704
	s_waitcnt lgkmcnt(1)
	v_mov_b32_e32 v14, v2
	s_waitcnt lgkmcnt(0)
	v_mov_b32_e32 v15, v18
	v_pk_fma_f32 v[6:7], v[106:107], v[14:15], v[6:7] op_sel_hi:[0,1,1]
	v_mov_b32_e32 v18, v3
	v_pk_fma_f32 v[2:3], v[16:17], v[18:19], v[6:7] op_sel_hi:[0,1,1]
	v_mov_b32_e32 v6, v4
	v_mov_b32_e32 v7, v20
	v_pk_fma_f32 v[2:3], v[108:109], v[6:7], v[2:3] op_sel_hi:[0,1,1]
	v_mov_b32_e32 v20, v5
	v_pk_fma_f32 v[6:7], v[24:25], v[20:21], v[2:3] op_sel_hi:[0,1,1]
	ds_read_b128 v[2:5], v146 offset:24624
	ds_read_b128 v[18:21], v146 offset:28720
	v_add_u32_e32 v146, 64, v146
	s_waitcnt lgkmcnt(1)
	v_mov_b32_e32 v14, v2
	s_waitcnt lgkmcnt(0)
	v_mov_b32_e32 v15, v18
	v_pk_fma_f32 v[6:7], v[104:105], v[14:15], v[6:7] op_sel_hi:[0,1,1]
	v_mov_b32_e32 v18, v3
	v_pk_fma_f32 v[2:3], v[12:13], v[18:19], v[6:7] op_sel_hi:[0,1,1]
	v_mov_b32_e32 v6, v4
	v_mov_b32_e32 v7, v20
	v_pk_fma_f32 v[2:3], v[102:103], v[6:7], v[2:3] op_sel_hi:[0,1,1]
	v_mov_b32_e32 v20, v5
	v_mov_b32_e32 v103, v48
	v_pk_fma_f32 v[100:101], v[48:49], v[20:21], v[2:3] op_sel_hi:[0,1,1]
	v_pk_mul_f32 v[2:3], v[102:103], v[10:11]
	s_nop 0
	v_add_f32_e32 v2, v17, v2
	v_add_f32_e32 v103, v2, v3
	s_andn2_b64 exec, exec, s[12:13]
	s_cbranch_execnz .LBB0_50
	s_or_b64 exec, exec, s[12:13]
	v_readlane_b32 s44, v253, 56
	v_readlane_b32 s45, v253, 57
	s_barrier
	ds_write2_b32 v133, v0, v1 offset1:32
	ds_write2_b32 v133, v8, v9 offset0:64 offset1:96
	ds_write2_b32 v133, v98, v99 offset0:128 offset1:160
	ds_write2_b32 v133, v100, v101 offset0:192 offset1:224
	ds_write_b32 v133, v103 offset:1024
	s_waitcnt lgkmcnt(0)
	s_barrier
	s_and_saveexec_b64 s[12:13], s[44:45]
	s_cbranch_execz .LBB0_54
	s_mul_i32 s11, s1, 0xc00
	s_add_i32 s14, s11, s10
	v_readlane_b32 s52, v253, 7
	v_or_b32_e32 v0, s14, v111
	v_readlane_b32 s53, v253, 8
	v_readlane_b32 s54, v253, 9
	v_readlane_b32 s55, v253, 10
	v_readlane_b32 s56, v253, 11
	v_readlane_b32 s57, v253, 12
	v_readlane_b32 s58, v253, 13
	v_readlane_b32 s59, v253, 14
	v_readlane_b32 s60, v253, 15
	v_readlane_b32 s61, v253, 16
	s_ashr_i32 s11, s10, 31
	v_ashrrev_i32_e32 v1, 31, v0
	v_readlane_b32 s62, v253, 17
	v_readlane_b32 s63, v253, 18
	s_mov_b32 s60, 0xb42fdfa7
	s_mov_b32 s58, 0x9037ab78
	s_mov_b32 s56, 0x252049c0
	s_mov_b32 s54, 0x6dc9c883
	s_mov_b32 s52, 0x6a5dcb37
	s_mul_hi_i32 s89, s1, 9
	s_mul_i32 s88, s1, 9
	s_mov_b32 s61, 0xbe5ae600
	s_mov_b32 s59, 0x3e21eeb6
	s_mov_b32 s57, 0xb97b839a
	s_mov_b32 s55, 0x3fe45f30
	s_mov_b32 s53, 0x3e5ade15
	v_lshl_add_u64 v[0:1], v[0:1], 2, s[62:63]
	v_lshl_add_u64 v[2:3], s[10:11], 2, v[50:51]
	s_mov_b64 s[10:11], 0
	v_mov_b32_e32 v4, v44
	v_readlane_b32 s64, v253, 19
	v_readlane_b32 s65, v253, 20
	v_readlane_b32 s66, v253, 21
	v_readlane_b32 s67, v253, 22
